# select fast path: 64-lane inclusive scan via DPP row_shr/row_bcast instead of six ds_bpermute round trips
# speedup vs baseline: 1.0010x; 1.0010x over previous
.LBB0_1436:
	s_lshl_b32 s0, s85, 2
	s_add_i32 s6, s0, 0
	v_mov_b32_e32 v0, s6
	s_waitcnt lgkmcnt(0)
	s_barrier
	ds_read_b32 v2, v0 offset:6336
	s_waitcnt lgkmcnt(0)
	v_cmp_gt_u32_e32 vcc, v17, v2
	s_nop 1
	v_cndmask_b32_e64 v0, 0, 1, vcc
	v_cmp_eq_u32_e32 vcc, v17, v2
	s_nop 1
	v_cndmask_b32_e32 v1, 0, v124, vcc
	v_cmp_eq_u32_e32 vcc, v16, v2
	v_or_b32_e32 v0, v1, v0
	s_nop 0
	v_cndmask_b32_e32 v1, 0, v124, vcc
	v_cmp_gt_u32_e32 vcc, v16, v2
	s_nop 1
	v_addc_co_u32_e32 v0, vcc, 0, v0, vcc
	v_cmp_eq_u32_e32 vcc, v15, v2
	s_nop 1
	v_cndmask_b32_e32 v3, 0, v124, vcc
	v_cmp_gt_u32_e32 vcc, v15, v2
	s_nop 1
	v_addc_co_u32_e32 v0, vcc, v0, v1, vcc
	v_cmp_eq_u32_e32 vcc, v14, v2
	s_nop 1
	v_cndmask_b32_e32 v1, 0, v124, vcc
	v_cmp_gt_u32_e32 vcc, v14, v2
	s_nop 1
	v_addc_co_u32_e32 v0, vcc, v0, v3, vcc
	v_cmp_eq_u32_e32 vcc, v13, v2
	s_nop 1
	v_cndmask_b32_e32 v3, 0, v124, vcc
	v_cmp_gt_u32_e32 vcc, v13, v2
	s_nop 1
	v_addc_co_u32_e32 v0, vcc, v0, v1, vcc
	v_cmp_eq_u32_e32 vcc, v12, v2
	s_nop 1
	v_cndmask_b32_e32 v1, 0, v124, vcc
	v_cmp_gt_u32_e32 vcc, v12, v2
	s_nop 1
	v_addc_co_u32_e32 v0, vcc, v0, v3, vcc
	v_cmp_eq_u32_e32 vcc, v11, v2
	s_nop 1
	v_cndmask_b32_e32 v3, 0, v124, vcc
	v_cmp_gt_u32_e32 vcc, v11, v2
	s_nop 1
	v_addc_co_u32_e32 v0, vcc, v0, v1, vcc
	v_cmp_eq_u32_e32 vcc, v10, v2
	s_nop 1
	v_cndmask_b32_e32 v1, 0, v124, vcc
	v_cmp_gt_u32_e32 vcc, v10, v2
	s_nop 1
	v_addc_co_u32_e32 v0, vcc, v0, v3, vcc
	v_add_u32_e32 v0, v0, v1
	v_mov_b32_e32 v1, v0
	s_nop 1
	v_add_u32_dpp v1, v1, v1 row_shr:1 row_mask:0xf bank_mask:0xf bound_ctrl:0
	s_nop 1
	v_add_u32_dpp v1, v1, v1 row_shr:2 row_mask:0xf bank_mask:0xf bound_ctrl:0
	s_nop 1
	v_add_u32_dpp v1, v1, v1 row_shr:4 row_mask:0xf bank_mask:0xf bound_ctrl:0
	s_nop 1
	v_add_u32_dpp v1, v1, v1 row_shr:8 row_mask:0xf bank_mask:0xf bound_ctrl:0
	s_nop 1
	v_add_u32_dpp v1, v1, v1 row_bcast:15 row_mask:0xa bank_mask:0xf
	s_nop 1
	v_add_u32_dpp v1, v1, v1 row_bcast:31 row_mask:0xc bank_mask:0xf
	s_nop 1
	v_cmp_eq_u32_e32 vcc, 63, v8
	s_and_saveexec_b64 s[0:1], vcc
	s_lshl_b32 s7, s84, 2
	s_add_i32 s7, s7, 0
	v_mov_b32_e32 v3, s7
	ds_write_b32 v3, v1 offset:6272
	s_or_b64 exec, exec, s[0:1]
	s_mul_i32 s0, s85, 12
	s_add_i32 s0, s6, s0
	v_mov_b32_e32 v3, s0
	s_waitcnt lgkmcnt(0)
	s_barrier
	ds_read_b128 v[4:7], v3 offset:6272
	s_bfe_u32 s0, s83, 0x20006
	s_cmp_lg_u32 s0, 0
	s_cselect_b64 vcc, -1, 0
	s_cmp_gt_u32 s0, 1
	s_waitcnt lgkmcnt(0)
	v_cndmask_b32_e32 v3, 0, v4, vcc
	s_cselect_b64 vcc, -1, 0
	s_cmp_eq_u32 s0, 3
	v_add_u32_e32 v4, v5, v4
	v_cndmask_b32_e32 v5, 0, v5, vcc
	s_cselect_b64 vcc, -1, 0
	v_add_u32_e32 v3, v5, v3
	v_add_u32_e32 v4, v4, v6
	v_sub_u32_e32 v0, v1, v0
	v_cndmask_b32_e32 v1, 0, v6, vcc
	s_add_i32 s0, s85, s82
	v_add_u32_e32 v3, v3, v1
	v_add_u32_e32 v1, v4, v7
	s_lshl_b32 s0, s0, 10
	v_add_u32_sdwa v1, v1, sext(v3) dst_sel:DWORD dst_unused:UNUSED_PAD src0_sel:WORD_0 src1_sel:WORD_1
	s_add_i32 s10, s0, 0
	s_lshl_b32 s0, s85, 12
	v_add_u32_sdwa v1, v1, sext(v0) dst_sel:DWORD dst_unused:UNUSED_PAD src0_sel:DWORD src1_sel:WORD_1
	v_add_u32_sdwa v0, v3, v0 dst_sel:DWORD dst_unused:UNUSED_PAD src0_sel:WORD_0 src1_sel:WORD_0
	s_add_i32 s11, s0, 0
	v_cmp_le_u32_e32 vcc, v17, v2
	s_and_saveexec_b64 s[0:1], vcc
	s_xor_b64 s[0:1], exec, s[0:1]
	s_cbranch_execz .LBB0_1444
	v_cmp_eq_u32_e32 vcc, v17, v2
	s_and_saveexec_b64 s[6:7], vcc
	s_cbranch_execz .LBB0_1443
	v_cmp_gt_i32_e32 vcc, s74, v1
	s_and_saveexec_b64 s[8:9], vcc
	s_cbranch_execz .LBB0_1442
	v_lshl_add_u32 v3, v9, 1, s11
	ds_read_u16 v3, v3 offset:26880
	v_lshl_add_u32 v4, v1, 2, s10
	s_waitcnt lgkmcnt(0)
	ds_write_b32 v4, v3 offset:6400
